# aj1 + nt hint on the gate/up epilogue HD stores (8 per tile)
# speedup vs baseline: 1.0117x; 1.0015x over previous
.Lepi_b2:
	v_pk_mul_f32 v[232:233], v[208:209], v[192:193]
	v_pk_mul_f32 v[234:235], v[210:211], v[192:193]
	v_pk_mul_f32 v[236:237], v[212:213], v[192:193]
	v_pk_mul_f32 v[238:239], v[214:215], v[192:193]
	v_exp_f32_e32 v232, v232
	v_exp_f32_e32 v233, v233
	v_exp_f32_e32 v234, v234
	v_exp_f32_e32 v235, v235
	v_exp_f32_e32 v236, v236
	v_exp_f32_e32 v237, v237
	v_exp_f32_e32 v238, v238
	v_exp_f32_e32 v239, v239
	v_pk_add_f32 v[232:233], v[232:233], v[194:195]
	v_pk_add_f32 v[234:235], v[234:235], v[194:195]
	v_pk_add_f32 v[236:237], v[236:237], v[194:195]
	v_pk_add_f32 v[238:239], v[238:239], v[194:195]
	v_rcp_f32_e32 v232, v232
	v_rcp_f32_e32 v233, v233
	v_rcp_f32_e32 v234, v234
	v_rcp_f32_e32 v235, v235
	v_rcp_f32_e32 v236, v236
	v_rcp_f32_e32 v237, v237
	v_rcp_f32_e32 v238, v238
	v_rcp_f32_e32 v239, v239
	v_pk_mul_f32 v[232:233], v[208:209], v[232:233]
	v_pk_mul_f32 v[234:235], v[210:211], v[234:235]
	v_pk_mul_f32 v[236:237], v[212:213], v[236:237]
	v_pk_mul_f32 v[238:239], v[214:215], v[238:239]
	v_pk_mul_f32 v[232:233], v[20:21], v[232:233]
	v_pk_mul_f32 v[234:235], v[22:23], v[234:235]
	v_pk_mul_f32 v[236:237], v[96:97], v[236:237]
	v_pk_mul_f32 v[238:239], v[98:99], v[238:239]
	v_cvt_pk_bf16_f32 v148, v232, v233
	v_cvt_pk_bf16_f32 v149, v234, v235
	v_cvt_pk_bf16_f32 v152, v236, v237
	v_cvt_pk_bf16_f32 v153, v238, v239
	v_pk_mul_f32 v[240:241], v[216:217], v[192:193]
	v_pk_mul_f32 v[242:243], v[218:219], v[192:193]
	v_pk_mul_f32 v[244:245], v[220:221], v[192:193]
	v_pk_mul_f32 v[246:247], v[222:223], v[192:193]
	v_exp_f32_e32 v240, v240
	v_exp_f32_e32 v241, v241
	v_exp_f32_e32 v242, v242
	v_exp_f32_e32 v243, v243
	v_exp_f32_e32 v244, v244
	v_exp_f32_e32 v245, v245
	v_exp_f32_e32 v246, v246
	v_exp_f32_e32 v247, v247
	v_pk_add_f32 v[240:241], v[240:241], v[194:195]
	v_pk_add_f32 v[242:243], v[242:243], v[194:195]
	v_pk_add_f32 v[244:245], v[244:245], v[194:195]
	v_pk_add_f32 v[246:247], v[246:247], v[194:195]
	v_rcp_f32_e32 v240, v240
	v_rcp_f32_e32 v241, v241
	v_rcp_f32_e32 v242, v242
	v_rcp_f32_e32 v243, v243
	v_rcp_f32_e32 v244, v244
	v_rcp_f32_e32 v245, v245
	v_rcp_f32_e32 v246, v246
	v_rcp_f32_e32 v247, v247
	v_pk_mul_f32 v[240:241], v[216:217], v[240:241]
	v_pk_mul_f32 v[242:243], v[218:219], v[242:243]
	v_pk_mul_f32 v[244:245], v[220:221], v[244:245]
	v_pk_mul_f32 v[246:247], v[222:223], v[246:247]
	v_pk_mul_f32 v[240:241], v[88:89], v[240:241]
	v_pk_mul_f32 v[242:243], v[90:91], v[242:243]
	v_pk_mul_f32 v[244:245], v[84:85], v[244:245]
	v_pk_mul_f32 v[246:247], v[86:87], v[246:247]
	v_cvt_pk_bf16_f32 v226, v240, v241
	v_cvt_pk_bf16_f32 v227, v242, v243
	v_cvt_pk_bf16_f32 v250, v244, v245
	v_cvt_pk_bf16_f32 v251, v246, v247
	v_mov_b64_e32 v[208:209], s[28:29]
	v_add_u32_e32 v196, 0, v181
	v_mad_i64_i32 v[196:197], s[20:21], v196, s2, v[208:209]
	v_lshl_add_u64 v[196:197], v[196:197], 0, v[182:183]
	global_store_dwordx4 v[196:197], v[146:149], off nt
	s_nop 1
	v_add_u32_e32 v198, 16, v181
	v_mad_i64_i32 v[198:199], s[20:21], v198, s2, v[208:209]
	v_lshl_add_u64 v[198:199], v[198:199], 0, v[182:183]
	global_store_dwordx4 v[198:199], v[150:153], off nt
	s_nop 1
	v_add_u32_e32 v196, 32, v181
	v_mad_i64_i32 v[196:197], s[20:21], v196, s2, v[208:209]
	v_lshl_add_u64 v[196:197], v[196:197], 0, v[182:183]
	global_store_dwordx4 v[196:197], v[224:227], off nt
	s_nop 1
	v_add_u32_e32 v198, 48, v181
	v_mad_i64_i32 v[198:199], s[20:21], v198, s2, v[208:209]
	v_lshl_add_u64 v[198:199], v[198:199], 0, v[182:183]
	global_store_dwordx4 v[198:199], v[248:251], off nt
	s_nop 1
	s_waitcnt lgkmcnt(0)
	v_cndmask_b32_e64 v184, 0, v128, s[14:15]
	v_cndmask_b32_e64 v185, 0, v129, s[14:15]
	v_cndmask_b32_e64 v186, 0, v130, s[14:15]
	v_cndmask_b32_e64 v187, 0, v131, s[14:15]
	v_cndmask_b32_e64 v188, 0, v136, s[16:17]
	v_cndmask_b32_e64 v189, 0, v137, s[16:17]
	v_cndmask_b32_e64 v190, 0, v138, s[16:17]
	v_cndmask_b32_e64 v191, 0, v139, s[16:17]
	v_pk_fma_f32 v[208:209], v[72:73], v[132:133], v[140:141]
	v_pk_fma_f32 v[210:211], v[74:75], v[134:135], v[142:143]
	v_pk_fma_f32 v[212:213], v[68:69], v[132:133], v[140:141]
	v_pk_fma_f32 v[214:215], v[70:71], v[134:135], v[142:143]
	v_pk_fma_f32 v[216:217], v[60:61], v[132:133], v[140:141]
	v_pk_fma_f32 v[218:219], v[62:63], v[134:135], v[142:143]
	v_pk_fma_f32 v[220:221], v[16:17], v[132:133], v[140:141]
	v_pk_fma_f32 v[222:223], v[18:19], v[134:135], v[142:143]
	v_fmac_f32_dpp v208, v72, v128 row_shr:1 row_mask:0xf bank_mask:0xf
	v_fmac_f32_dpp v209, v73, v129 row_shr:1 row_mask:0xf bank_mask:0xf
	v_fmac_f32_dpp v210, v74, v130 row_shr:1 row_mask:0xf bank_mask:0xf
	v_fmac_f32_dpp v211, v75, v131 row_shr:1 row_mask:0xf bank_mask:0xf
	v_fmac_f32_dpp v212, v68, v128 row_shr:1 row_mask:0xf bank_mask:0xf
	v_fmac_f32_dpp v213, v69, v129 row_shr:1 row_mask:0xf bank_mask:0xf
	v_fmac_f32_dpp v214, v70, v130 row_shr:1 row_mask:0xf bank_mask:0xf
	v_fmac_f32_dpp v215, v71, v131 row_shr:1 row_mask:0xf bank_mask:0xf
	v_fmac_f32_dpp v216, v60, v128 row_shr:1 row_mask:0xf bank_mask:0xf
	v_fmac_f32_dpp v217, v61, v129 row_shr:1 row_mask:0xf bank_mask:0xf
	v_fmac_f32_dpp v218, v62, v130 row_shr:1 row_mask:0xf bank_mask:0xf
	v_fmac_f32_dpp v219, v63, v131 row_shr:1 row_mask:0xf bank_mask:0xf
	v_fmac_f32_dpp v220, v16, v128 row_shr:1 row_mask:0xf bank_mask:0xf
	v_fmac_f32_dpp v221, v17, v129 row_shr:1 row_mask:0xf bank_mask:0xf
	v_fmac_f32_dpp v222, v18, v130 row_shr:1 row_mask:0xf bank_mask:0xf
	v_fmac_f32_dpp v223, v19, v131 row_shr:1 row_mask:0xf bank_mask:0xf
	v_fmac_f32_dpp v208, v72, v136 row_shl:1 row_mask:0xf bank_mask:0xf
	v_fmac_f32_dpp v209, v73, v137 row_shl:1 row_mask:0xf bank_mask:0xf
	v_fmac_f32_dpp v210, v74, v138 row_shl:1 row_mask:0xf bank_mask:0xf
	v_fmac_f32_dpp v211, v75, v139 row_shl:1 row_mask:0xf bank_mask:0xf
	v_fmac_f32_dpp v212, v68, v136 row_shl:1 row_mask:0xf bank_mask:0xf
	v_fmac_f32_dpp v213, v69, v137 row_shl:1 row_mask:0xf bank_mask:0xf
	v_fmac_f32_dpp v214, v70, v138 row_shl:1 row_mask:0xf bank_mask:0xf
	v_fmac_f32_dpp v215, v71, v139 row_shl:1 row_mask:0xf bank_mask:0xf
	v_fmac_f32_dpp v216, v60, v136 row_shl:1 row_mask:0xf bank_mask:0xf
	v_fmac_f32_dpp v217, v61, v137 row_shl:1 row_mask:0xf bank_mask:0xf
	v_fmac_f32_dpp v218, v62, v138 row_shl:1 row_mask:0xf bank_mask:0xf
	v_fmac_f32_dpp v219, v63, v139 row_shl:1 row_mask:0xf bank_mask:0xf
	v_fmac_f32_dpp v220, v16, v136 row_shl:1 row_mask:0xf bank_mask:0xf
	v_fmac_f32_dpp v221, v17, v137 row_shl:1 row_mask:0xf bank_mask:0xf
	v_fmac_f32_dpp v222, v18, v138 row_shl:1 row_mask:0xf bank_mask:0xf
	v_fmac_f32_dpp v223, v19, v139 row_shl:1 row_mask:0xf bank_mask:0xf
	v_fmac_f32_e32 v208, v200, v184
	v_fmac_f32_e32 v209, v201, v185
	v_fmac_f32_e32 v210, v202, v186
	v_fmac_f32_e32 v211, v203, v187
	v_fmac_f32_dpp v212, v72, v184 row_ror:1 row_mask:0xf bank_mask:0xf
	v_fmac_f32_dpp v213, v73, v185 row_ror:1 row_mask:0xf bank_mask:0xf
	v_fmac_f32_dpp v214, v74, v186 row_ror:1 row_mask:0xf bank_mask:0xf
	v_fmac_f32_dpp v215, v75, v187 row_ror:1 row_mask:0xf bank_mask:0xf
	v_fmac_f32_dpp v216, v68, v184 row_ror:1 row_mask:0xf bank_mask:0xf
	v_fmac_f32_dpp v217, v69, v185 row_ror:1 row_mask:0xf bank_mask:0xf
	v_fmac_f32_dpp v218, v70, v186 row_ror:1 row_mask:0xf bank_mask:0xf
	v_fmac_f32_dpp v219, v71, v187 row_ror:1 row_mask:0xf bank_mask:0xf
	v_fmac_f32_dpp v220, v60, v184 row_ror:1 row_mask:0xf bank_mask:0xf
	v_fmac_f32_dpp v221, v61, v185 row_ror:1 row_mask:0xf bank_mask:0xf
	v_fmac_f32_dpp v222, v62, v186 row_ror:1 row_mask:0xf bank_mask:0xf
	v_fmac_f32_dpp v223, v63, v187 row_ror:1 row_mask:0xf bank_mask:0xf
	v_fmac_f32_dpp v208, v68, v188 row_ror:15 row_mask:0xf bank_mask:0xf
	v_fmac_f32_dpp v209, v69, v189 row_ror:15 row_mask:0xf bank_mask:0xf
	v_fmac_f32_dpp v210, v70, v190 row_ror:15 row_mask:0xf bank_mask:0xf
	v_fmac_f32_dpp v211, v71, v191 row_ror:15 row_mask:0xf bank_mask:0xf
	v_fmac_f32_dpp v212, v60, v188 row_ror:15 row_mask:0xf bank_mask:0xf
	v_fmac_f32_dpp v213, v61, v189 row_ror:15 row_mask:0xf bank_mask:0xf
	v_fmac_f32_dpp v214, v62, v190 row_ror:15 row_mask:0xf bank_mask:0xf
	v_fmac_f32_dpp v215, v63, v191 row_ror:15 row_mask:0xf bank_mask:0xf
	v_fmac_f32_dpp v216, v16, v188 row_ror:15 row_mask:0xf bank_mask:0xf
	v_fmac_f32_dpp v217, v17, v189 row_ror:15 row_mask:0xf bank_mask:0xf
	v_fmac_f32_dpp v218, v18, v190 row_ror:15 row_mask:0xf bank_mask:0xf
	v_fmac_f32_dpp v219, v19, v191 row_ror:15 row_mask:0xf bank_mask:0xf
	v_fmac_f32_e32 v220, v204, v188
	v_fmac_f32_e32 v221, v205, v189
	v_fmac_f32_e32 v222, v206, v190
	v_fmac_f32_e32 v223, v207, v191
	ds_read_b128 v[128:131], v174 offset:16
	ds_read_b128 v[132:135], v174 offset:528
	ds_read_b128 v[136:139], v174 offset:1040
	ds_read_b128 v[140:143], v174 offset:1552
	v_mov_b64_e32 v[200:201], 0
	v_mov_b64_e32 v[202:203], 0
	v_mov_b64_e32 v[204:205], 0
	v_mov_b64_e32 v[206:207], 0
	s_and_b64 vcc, exec, s[52:53]
	s_cbranch_vccz .Lepi_a3
	ds_read_b128 v[200:203], v172 offset:1552

.Lepi_b3:
	v_pk_mul_f32 v[232:233], v[208:209], v[192:193]
	v_pk_mul_f32 v[234:235], v[210:211], v[192:193]
	v_pk_mul_f32 v[236:237], v[212:213], v[192:193]
	v_pk_mul_f32 v[238:239], v[214:215], v[192:193]
	v_exp_f32_e32 v232, v232
	v_exp_f32_e32 v233, v233
	v_exp_f32_e32 v234, v234
	v_exp_f32_e32 v235, v235
	v_exp_f32_e32 v236, v236
	v_exp_f32_e32 v237, v237
	v_exp_f32_e32 v238, v238
	v_exp_f32_e32 v239, v239
	v_pk_add_f32 v[232:233], v[232:233], v[194:195]
	v_pk_add_f32 v[234:235], v[234:235], v[194:195]
	v_pk_add_f32 v[236:237], v[236:237], v[194:195]
	v_pk_add_f32 v[238:239], v[238:239], v[194:195]
	v_rcp_f32_e32 v232, v232
	v_rcp_f32_e32 v233, v233
	v_rcp_f32_e32 v234, v234
	v_rcp_f32_e32 v235, v235
	v_rcp_f32_e32 v236, v236
	v_rcp_f32_e32 v237, v237
	v_rcp_f32_e32 v238, v238
	v_rcp_f32_e32 v239, v239
	v_pk_mul_f32 v[232:233], v[208:209], v[232:233]
	v_pk_mul_f32 v[234:235], v[210:211], v[234:235]
	v_pk_mul_f32 v[236:237], v[212:213], v[236:237]
	v_pk_mul_f32 v[238:239], v[214:215], v[238:239]
	v_pk_mul_f32 v[232:233], v[76:77], v[232:233]
	v_pk_mul_f32 v[234:235], v[78:79], v[234:235]
	v_pk_mul_f32 v[236:237], v[64:65], v[236:237]
	v_pk_mul_f32 v[238:239], v[66:67], v[238:239]
	v_cvt_pk_bf16_f32 v146, v232, v233
	v_cvt_pk_bf16_f32 v147, v234, v235
	v_cvt_pk_bf16_f32 v150, v236, v237
	v_cvt_pk_bf16_f32 v151, v238, v239
	v_pk_mul_f32 v[240:241], v[216:217], v[192:193]
	v_pk_mul_f32 v[242:243], v[218:219], v[192:193]
	v_pk_mul_f32 v[244:245], v[220:221], v[192:193]
	v_pk_mul_f32 v[246:247], v[222:223], v[192:193]
	v_exp_f32_e32 v240, v240
	v_exp_f32_e32 v241, v241
	v_exp_f32_e32 v242, v242
	v_exp_f32_e32 v243, v243
	v_exp_f32_e32 v244, v244
	v_exp_f32_e32 v245, v245
	v_exp_f32_e32 v246, v246
	v_exp_f32_e32 v247, v247
	v_pk_add_f32 v[240:241], v[240:241], v[194:195]
	v_pk_add_f32 v[242:243], v[242:243], v[194:195]
	v_pk_add_f32 v[244:245], v[244:245], v[194:195]
	v_pk_add_f32 v[246:247], v[246:247], v[194:195]
	v_rcp_f32_e32 v240, v240
	v_rcp_f32_e32 v241, v241
	v_rcp_f32_e32 v242, v242
	v_rcp_f32_e32 v243, v243
	v_rcp_f32_e32 v244, v244
	v_rcp_f32_e32 v245, v245
	v_rcp_f32_e32 v246, v246
	v_rcp_f32_e32 v247, v247
	v_pk_mul_f32 v[240:241], v[216:217], v[240:241]
	v_pk_mul_f32 v[242:243], v[218:219], v[242:243]
	v_pk_mul_f32 v[244:245], v[220:221], v[244:245]
	v_pk_mul_f32 v[246:247], v[222:223], v[246:247]
	v_pk_mul_f32 v[240:241], v[56:57], v[240:241]
	v_pk_mul_f32 v[242:243], v[58:59], v[242:243]
	v_pk_mul_f32 v[244:245], v[8:9], v[244:245]
	v_pk_mul_f32 v[246:247], v[10:11], v[246:247]
	v_cvt_pk_bf16_f32 v224, v240, v241
	v_cvt_pk_bf16_f32 v225, v242, v243
	v_cvt_pk_bf16_f32 v248, v244, v245
	v_cvt_pk_bf16_f32 v249, v246, v247
	s_waitcnt lgkmcnt(0)
	v_cndmask_b32_e64 v184, 0, v128, s[14:15]
	v_cndmask_b32_e64 v185, 0, v129, s[14:15]
	v_cndmask_b32_e64 v186, 0, v130, s[14:15]
	v_cndmask_b32_e64 v187, 0, v131, s[14:15]
	v_cndmask_b32_e64 v188, 0, v136, s[16:17]
	v_cndmask_b32_e64 v189, 0, v137, s[16:17]
	v_cndmask_b32_e64 v190, 0, v138, s[16:17]
	v_cndmask_b32_e64 v191, 0, v139, s[16:17]
	v_pk_fma_f32 v[208:209], v[48:49], v[132:133], v[140:141]
	v_pk_fma_f32 v[210:211], v[50:51], v[134:135], v[142:143]
	v_pk_fma_f32 v[212:213], v[44:45], v[132:133], v[140:141]
	v_pk_fma_f32 v[214:215], v[46:47], v[134:135], v[142:143]
	v_pk_fma_f32 v[216:217], v[36:37], v[132:133], v[140:141]
	v_pk_fma_f32 v[218:219], v[38:39], v[134:135], v[142:143]
	v_pk_fma_f32 v[220:221], v[0:1], v[132:133], v[140:141]
	v_pk_fma_f32 v[222:223], v[2:3], v[134:135], v[142:143]
	v_fmac_f32_dpp v208, v48, v128 row_shr:1 row_mask:0xf bank_mask:0xf
	v_fmac_f32_dpp v209, v49, v129 row_shr:1 row_mask:0xf bank_mask:0xf
	v_fmac_f32_dpp v210, v50, v130 row_shr:1 row_mask:0xf bank_mask:0xf
	v_fmac_f32_dpp v211, v51, v131 row_shr:1 row_mask:0xf bank_mask:0xf
	v_fmac_f32_dpp v212, v44, v128 row_shr:1 row_mask:0xf bank_mask:0xf
	v_fmac_f32_dpp v213, v45, v129 row_shr:1 row_mask:0xf bank_mask:0xf
	v_fmac_f32_dpp v214, v46, v130 row_shr:1 row_mask:0xf bank_mask:0xf
	v_fmac_f32_dpp v215, v47, v131 row_shr:1 row_mask:0xf bank_mask:0xf
	v_fmac_f32_dpp v216, v36, v128 row_shr:1 row_mask:0xf bank_mask:0xf
	v_fmac_f32_dpp v217, v37, v129 row_shr:1 row_mask:0xf bank_mask:0xf
	v_fmac_f32_dpp v218, v38, v130 row_shr:1 row_mask:0xf bank_mask:0xf
	v_fmac_f32_dpp v219, v39, v131 row_shr:1 row_mask:0xf bank_mask:0xf
	v_fmac_f32_dpp v220, v0, v128 row_shr:1 row_mask:0xf bank_mask:0xf
	v_fmac_f32_dpp v221, v1, v129 row_shr:1 row_mask:0xf bank_mask:0xf
	v_fmac_f32_dpp v222, v2, v130 row_shr:1 row_mask:0xf bank_mask:0xf
	v_fmac_f32_dpp v223, v3, v131 row_shr:1 row_mask:0xf bank_mask:0xf
	v_fmac_f32_dpp v208, v48, v136 row_shl:1 row_mask:0xf bank_mask:0xf
	v_fmac_f32_dpp v209, v49, v137 row_shl:1 row_mask:0xf bank_mask:0xf
	v_fmac_f32_dpp v210, v50, v138 row_shl:1 row_mask:0xf bank_mask:0xf
	v_fmac_f32_dpp v211, v51, v139 row_shl:1 row_mask:0xf bank_mask:0xf
	v_fmac_f32_dpp v212, v44, v136 row_shl:1 row_mask:0xf bank_mask:0xf
	v_fmac_f32_dpp v213, v45, v137 row_shl:1 row_mask:0xf bank_mask:0xf
	v_fmac_f32_dpp v214, v46, v138 row_shl:1 row_mask:0xf bank_mask:0xf
	v_fmac_f32_dpp v215, v47, v139 row_shl:1 row_mask:0xf bank_mask:0xf
	v_fmac_f32_dpp v216, v36, v136 row_shl:1 row_mask:0xf bank_mask:0xf
	v_fmac_f32_dpp v217, v37, v137 row_shl:1 row_mask:0xf bank_mask:0xf
	v_fmac_f32_dpp v218, v38, v138 row_shl:1 row_mask:0xf bank_mask:0xf
	v_fmac_f32_dpp v219, v39, v139 row_shl:1 row_mask:0xf bank_mask:0xf
	v_fmac_f32_dpp v220, v0, v136 row_shl:1 row_mask:0xf bank_mask:0xf
	v_fmac_f32_dpp v221, v1, v137 row_shl:1 row_mask:0xf bank_mask:0xf
	v_fmac_f32_dpp v222, v2, v138 row_shl:1 row_mask:0xf bank_mask:0xf
	v_fmac_f32_dpp v223, v3, v139 row_shl:1 row_mask:0xf bank_mask:0xf
	v_fmac_f32_e32 v208, v200, v184
	v_fmac_f32_e32 v209, v201, v185
	v_fmac_f32_e32 v210, v202, v186
	v_fmac_f32_e32 v211, v203, v187
	v_fmac_f32_dpp v212, v48, v184 row_ror:1 row_mask:0xf bank_mask:0xf
	v_fmac_f32_dpp v213, v49, v185 row_ror:1 row_mask:0xf bank_mask:0xf
	v_fmac_f32_dpp v214, v50, v186 row_ror:1 row_mask:0xf bank_mask:0xf
	v_fmac_f32_dpp v215, v51, v187 row_ror:1 row_mask:0xf bank_mask:0xf
	v_fmac_f32_dpp v216, v44, v184 row_ror:1 row_mask:0xf bank_mask:0xf
	v_fmac_f32_dpp v217, v45, v185 row_ror:1 row_mask:0xf bank_mask:0xf
	v_fmac_f32_dpp v218, v46, v186 row_ror:1 row_mask:0xf bank_mask:0xf
	v_fmac_f32_dpp v219, v47, v187 row_ror:1 row_mask:0xf bank_mask:0xf
	v_fmac_f32_dpp v220, v36, v184 row_ror:1 row_mask:0xf bank_mask:0xf
	v_fmac_f32_dpp v221, v37, v185 row_ror:1 row_mask:0xf bank_mask:0xf
	v_fmac_f32_dpp v222, v38, v186 row_ror:1 row_mask:0xf bank_mask:0xf
	v_fmac_f32_dpp v223, v39, v187 row_ror:1 row_mask:0xf bank_mask:0xf
	v_fmac_f32_dpp v208, v44, v188 row_ror:15 row_mask:0xf bank_mask:0xf
	v_fmac_f32_dpp v209, v45, v189 row_ror:15 row_mask:0xf bank_mask:0xf
	v_fmac_f32_dpp v210, v46, v190 row_ror:15 row_mask:0xf bank_mask:0xf
	v_fmac_f32_dpp v211, v47, v191 row_ror:15 row_mask:0xf bank_mask:0xf
	v_fmac_f32_dpp v212, v36, v188 row_ror:15 row_mask:0xf bank_mask:0xf
	v_fmac_f32_dpp v213, v37, v189 row_ror:15 row_mask:0xf bank_mask:0xf
	v_fmac_f32_dpp v214, v38, v190 row_ror:15 row_mask:0xf bank_mask:0xf
	v_fmac_f32_dpp v215, v39, v191 row_ror:15 row_mask:0xf bank_mask:0xf
	v_fmac_f32_dpp v216, v0, v188 row_ror:15 row_mask:0xf bank_mask:0xf
	v_fmac_f32_dpp v217, v1, v189 row_ror:15 row_mask:0xf bank_mask:0xf
	v_fmac_f32_dpp v218, v2, v190 row_ror:15 row_mask:0xf bank_mask:0xf
	v_fmac_f32_dpp v219, v3, v191 row_ror:15 row_mask:0xf bank_mask:0xf
	v_fmac_f32_e32 v220, v204, v188
	v_fmac_f32_e32 v221, v205, v189
	v_fmac_f32_e32 v222, v206, v190
	v_fmac_f32_e32 v223, v207, v191
	v_pk_mul_f32 v[232:233], v[208:209], v[192:193]
	v_pk_mul_f32 v[234:235], v[210:211], v[192:193]
	v_pk_mul_f32 v[236:237], v[212:213], v[192:193]
	v_pk_mul_f32 v[238:239], v[214:215], v[192:193]
	v_exp_f32_e32 v232, v232
	v_exp_f32_e32 v233, v233
	v_exp_f32_e32 v234, v234
	v_exp_f32_e32 v235, v235
	v_exp_f32_e32 v236, v236
	v_exp_f32_e32 v237, v237
	v_exp_f32_e32 v238, v238
	v_exp_f32_e32 v239, v239
	v_pk_add_f32 v[232:233], v[232:233], v[194:195]
	v_pk_add_f32 v[234:235], v[234:235], v[194:195]
	v_pk_add_f32 v[236:237], v[236:237], v[194:195]
	v_pk_add_f32 v[238:239], v[238:239], v[194:195]
	v_rcp_f32_e32 v232, v232
	v_rcp_f32_e32 v233, v233
	v_rcp_f32_e32 v234, v234
	v_rcp_f32_e32 v235, v235
	v_rcp_f32_e32 v236, v236
	v_rcp_f32_e32 v237, v237
	v_rcp_f32_e32 v238, v238
	v_rcp_f32_e32 v239, v239
	v_pk_mul_f32 v[232:233], v[208:209], v[232:233]
	v_pk_mul_f32 v[234:235], v[210:211], v[234:235]
	v_pk_mul_f32 v[236:237], v[212:213], v[236:237]
	v_pk_mul_f32 v[238:239], v[214:215], v[238:239]
	v_pk_mul_f32 v[232:233], v[52:53], v[232:233]
	v_pk_mul_f32 v[234:235], v[54:55], v[234:235]
	v_pk_mul_f32 v[236:237], v[40:41], v[236:237]
	v_pk_mul_f32 v[238:239], v[42:43], v[238:239]
	v_cvt_pk_bf16_f32 v148, v232, v233
	v_cvt_pk_bf16_f32 v149, v234, v235
	v_cvt_pk_bf16_f32 v152, v236, v237
	v_cvt_pk_bf16_f32 v153, v238, v239
	v_pk_mul_f32 v[240:241], v[216:217], v[192:193]
	v_pk_mul_f32 v[242:243], v[218:219], v[192:193]
	v_pk_mul_f32 v[244:245], v[220:221], v[192:193]
	v_pk_mul_f32 v[246:247], v[222:223], v[192:193]
	v_exp_f32_e32 v240, v240
	v_exp_f32_e32 v241, v241
	v_exp_f32_e32 v242, v242
	v_exp_f32_e32 v243, v243
	v_exp_f32_e32 v244, v244
	v_exp_f32_e32 v245, v245
	v_exp_f32_e32 v246, v246
	v_exp_f32_e32 v247, v247
	v_pk_add_f32 v[240:241], v[240:241], v[194:195]
	v_pk_add_f32 v[242:243], v[242:243], v[194:195]
	v_pk_add_f32 v[244:245], v[244:245], v[194:195]
	v_pk_add_f32 v[246:247], v[246:247], v[194:195]
	v_rcp_f32_e32 v240, v240
	v_rcp_f32_e32 v241, v241
	v_rcp_f32_e32 v242, v242
	v_rcp_f32_e32 v243, v243
	v_rcp_f32_e32 v244, v244
	v_rcp_f32_e32 v245, v245
	v_rcp_f32_e32 v246, v246
	v_rcp_f32_e32 v247, v247
	v_pk_mul_f32 v[240:241], v[216:217], v[240:241]
	v_pk_mul_f32 v[242:243], v[218:219], v[242:243]
	v_pk_mul_f32 v[244:245], v[220:221], v[244:245]
	v_pk_mul_f32 v[246:247], v[222:223], v[246:247]
	v_pk_mul_f32 v[240:241], v[32:33], v[240:241]
	v_pk_mul_f32 v[242:243], v[34:35], v[242:243]
	v_pk_mul_f32 v[244:245], v[4:5], v[244:245]
	v_pk_mul_f32 v[246:247], v[6:7], v[246:247]
	v_cvt_pk_bf16_f32 v226, v240, v241
	v_cvt_pk_bf16_f32 v227, v242, v243
	v_cvt_pk_bf16_f32 v250, v244, v245
	v_cvt_pk_bf16_f32 v251, v246, v247
	v_mov_b64_e32 v[208:209], s[28:29]
	v_add_u32_e32 v196, 128, v181
	v_mad_i64_i32 v[196:197], s[20:21], v196, s2, v[208:209]
	v_lshl_add_u64 v[196:197], v[196:197], 0, v[182:183]
	global_store_dwordx4 v[196:197], v[146:149], off nt
	s_nop 1
	v_add_u32_e32 v198, 144, v181
	v_mad_i64_i32 v[198:199], s[20:21], v198, s2, v[208:209]
	v_lshl_add_u64 v[198:199], v[198:199], 0, v[182:183]
	global_store_dwordx4 v[198:199], v[150:153], off nt
	s_nop 1
	v_add_u32_e32 v196, 160, v181
	v_mad_i64_i32 v[196:197], s[20:21], v196, s2, v[208:209]
	v_lshl_add_u64 v[196:197], v[196:197], 0, v[182:183]
	global_store_dwordx4 v[196:197], v[224:227], off nt
	s_nop 1
	v_add_u32_e32 v198, 176, v181
	v_mad_i64_i32 v[198:199], s[20:21], v198, s2, v[208:209]
	v_lshl_add_u64 v[198:199], v[198:199], 0, v[182:183]
	global_store_dwordx4 v[198:199], v[248:251], off nt
	s_nop 1
	v_or_b32_e32 v110, s22, v167
	v_ashrrev_i32_e32 v111, 31, v110
	s_and_saveexec_b64 s[20:21], s[4:5]
	s_cbranch_execnz .LBB0_1018
	s_or_b64 exec, exec, s[20:21]
	s_and_saveexec_b64 s[20:21], s[26:27]
	s_cbranch_execnz .LBB0_1021
